# softmax: lane-local max tested against ref+8 first; cross-half max exchange (bpermute+wait) only on the rare reference-update path
# speedup vs baseline: 1.0407x; 1.0070x over previous
.Lj3ld_norka:
	s_or_b64 exec, exec, s[6:7]
	s_waitcnt lgkmcnt(0)
	v_mfma_f32_32x32x16_bf16 v[146:161], v[240:243], v[246:249], v[146:161]
	s_nop 11
	v_pk_add_f32 v[146:147], v[130:131], v[146:147]
	v_pk_add_f32 v[132:133], v[132:133], v[148:149]
	v_max_f32_e32 v130, v146, v147
	v_pk_add_f32 v[134:135], v[134:135], v[150:151]
	v_max3_f32 v130, v130, v132, v133
	v_pk_add_f32 v[136:137], v[136:137], v[152:153]
	v_max3_f32 v130, v130, v134, v135
	v_pk_add_f32 v[138:139], v[138:139], v[154:155]
	v_max3_f32 v130, v130, v136, v137
	v_pk_add_f32 v[140:141], v[140:141], v[156:157]
	v_max3_f32 v130, v130, v138, v139
	v_pk_add_f32 v[142:143], v[142:143], v[158:159]
	v_max3_f32 v130, v130, v140, v141
	v_pk_add_f32 v[144:145], v[144:145], v[160:161]
	v_max3_f32 v130, v130, v142, v143
	v_max3_f32 v130, v130, v144, v145
	v_sub_f32_e32 v131, v230, v130
	v_cmp_gt_f32_e32 vcc, 0xc1000000, v131
	s_cbranch_vccnz .Llazy0_full
	ds_read_b64_tr_b16 v[232:233], v222
	ds_read_b64_tr_b16 v[234:235], v222 offset:4736
	ds_read_b64_tr_b16 v[236:237], v222 offset:64
	ds_read_b64_tr_b16 v[238:239], v222 offset:4800
	ds_read_b64_tr_b16 v[240:241], v222 offset:128
	ds_read_b64_tr_b16 v[242:243], v222 offset:4864
	ds_read_b64_tr_b16 v[246:247], v222 offset:192
	ds_read_b64_tr_b16 v[248:249], v222 offset:4928
	v_mov_b32_e32 v229, v230
	v_mov_b32_e32 v130, 1.0
	s_branch .LBB0_946
.Llazy0_full:
	v_mbcnt_hi_u32_b32 v131, -1, v217
	v_and_b32_e32 v149, 64, v131
	v_xor_b32_e32 v148, 32, v131
	v_add_u32_e32 v149, 64, v149
	v_cmp_lt_i32_e32 vcc, v148, v149
	s_nop 1
	v_cndmask_b32_e32 v131, v131, v148, vcc
	v_lshlrev_b32_e32 v131, 2, v131
	ds_bpermute_b32 v131, v131, v130
	s_waitcnt lgkmcnt(0)
	ds_read_b64_tr_b16 v[232:233], v222
	ds_read_b64_tr_b16 v[234:235], v222 offset:4736
	ds_read_b64_tr_b16 v[236:237], v222 offset:64
	ds_read_b64_tr_b16 v[238:239], v222 offset:4800
	ds_read_b64_tr_b16 v[240:241], v222 offset:128
	ds_read_b64_tr_b16 v[242:243], v222 offset:4864
	ds_read_b64_tr_b16 v[246:247], v222 offset:192
	ds_read_b64_tr_b16 v[248:249], v222 offset:4928
	v_max3_f32 v229, v230, v130, v131
	v_sub_f32_e32 v130, v230, v229
	v_exp_f32_e32 v130, v130
	s_nop 0
	v_cmp_neq_f32_e32 vcc, 1.0, v130
	s_cbranch_vccz .LBB0_946
	v_pk_mul_f32 v[128:129], v[128:129], v[130:131] op_sel_hi:[1,0]
	v_pk_mul_f32 v[126:127], v[126:127], v[130:131] op_sel_hi:[1,0]
	v_pk_mul_f32 v[124:125], v[124:125], v[130:131] op_sel_hi:[1,0]
	v_pk_mul_f32 v[122:123], v[122:123], v[130:131] op_sel_hi:[1,0]
	v_pk_mul_f32 v[120:121], v[120:121], v[130:131] op_sel_hi:[1,0]
	v_pk_mul_f32 v[118:119], v[118:119], v[130:131] op_sel_hi:[1,0]
	v_pk_mul_f32 v[116:117], v[116:117], v[130:131] op_sel_hi:[1,0]
	v_pk_mul_f32 v[114:115], v[114:115], v[130:131] op_sel_hi:[1,0]
	v_pk_mul_f32 v[112:113], v[112:113], v[130:131] op_sel_hi:[1,0]
	v_pk_mul_f32 v[110:111], v[110:111], v[130:131] op_sel_hi:[1,0]
	v_pk_mul_f32 v[108:109], v[108:109], v[130:131] op_sel_hi:[1,0]
	v_pk_mul_f32 v[106:107], v[106:107], v[130:131] op_sel_hi:[1,0]
	v_pk_mul_f32 v[104:105], v[104:105], v[130:131] op_sel_hi:[1,0]
	v_pk_mul_f32 v[102:103], v[102:103], v[130:131] op_sel_hi:[1,0]
	v_pk_mul_f32 v[100:101], v[100:101], v[130:131] op_sel_hi:[1,0]
	v_pk_mul_f32 v[98:99], v[98:99], v[130:131] op_sel_hi:[1,0]
	v_pk_mul_f32 v[96:97], v[96:97], v[130:131] op_sel_hi:[1,0]
	v_pk_mul_f32 v[94:95], v[94:95], v[130:131] op_sel_hi:[1,0]
	v_pk_mul_f32 v[92:93], v[92:93], v[130:131] op_sel_hi:[1,0]
	v_pk_mul_f32 v[90:91], v[90:91], v[130:131] op_sel_hi:[1,0]
	v_pk_mul_f32 v[88:89], v[88:89], v[130:131] op_sel_hi:[1,0]
	v_pk_mul_f32 v[86:87], v[86:87], v[130:131] op_sel_hi:[1,0]
	v_pk_mul_f32 v[84:85], v[84:85], v[130:131] op_sel_hi:[1,0]
	v_pk_mul_f32 v[82:83], v[82:83], v[130:131] op_sel_hi:[1,0]
	v_pk_mul_f32 v[80:81], v[80:81], v[130:131] op_sel_hi:[1,0]
	v_pk_mul_f32 v[78:79], v[78:79], v[130:131] op_sel_hi:[1,0]
	v_pk_mul_f32 v[76:77], v[76:77], v[130:131] op_sel_hi:[1,0]
	v_pk_mul_f32 v[74:75], v[74:75], v[130:131] op_sel_hi:[1,0]
	v_pk_mul_f32 v[72:73], v[72:73], v[130:131] op_sel_hi:[1,0]
	v_pk_mul_f32 v[70:71], v[70:71], v[130:131] op_sel_hi:[1,0]
	v_pk_mul_f32 v[68:69], v[68:69], v[130:131] op_sel_hi:[1,0]
	v_pk_mul_f32 v[66:67], v[66:67], v[130:131] op_sel_hi:[1,0]
	v_pk_mul_f32 v[64:65], v[64:65], v[130:131] op_sel_hi:[1,0]
	v_pk_mul_f32 v[62:63], v[62:63], v[130:131] op_sel_hi:[1,0]
	v_pk_mul_f32 v[60:61], v[60:61], v[130:131] op_sel_hi:[1,0]
	v_pk_mul_f32 v[58:59], v[58:59], v[130:131] op_sel_hi:[1,0]
	v_pk_mul_f32 v[56:57], v[56:57], v[130:131] op_sel_hi:[1,0]
	v_pk_mul_f32 v[54:55], v[54:55], v[130:131] op_sel_hi:[1,0]
	v_pk_mul_f32 v[52:53], v[52:53], v[130:131] op_sel_hi:[1,0]
	v_pk_mul_f32 v[50:51], v[50:51], v[130:131] op_sel_hi:[1,0]
	v_pk_mul_f32 v[48:49], v[48:49], v[130:131] op_sel_hi:[1,0]
	v_pk_mul_f32 v[46:47], v[46:47], v[130:131] op_sel_hi:[1,0]
	v_pk_mul_f32 v[44:45], v[44:45], v[130:131] op_sel_hi:[1,0]
	v_pk_mul_f32 v[42:43], v[42:43], v[130:131] op_sel_hi:[1,0]
	v_pk_mul_f32 v[40:41], v[40:41], v[130:131] op_sel_hi:[1,0]
	v_pk_mul_f32 v[38:39], v[38:39], v[130:131] op_sel_hi:[1,0]
	v_pk_mul_f32 v[36:37], v[36:37], v[130:131] op_sel_hi:[1,0]
	v_pk_mul_f32 v[34:35], v[34:35], v[130:131] op_sel_hi:[1,0]
	v_pk_mul_f32 v[32:33], v[32:33], v[130:131] op_sel_hi:[1,0]
	v_pk_mul_f32 v[30:31], v[30:31], v[130:131] op_sel_hi:[1,0]
	v_pk_mul_f32 v[28:29], v[28:29], v[130:131] op_sel_hi:[1,0]
	v_pk_mul_f32 v[26:27], v[26:27], v[130:131] op_sel_hi:[1,0]
	v_pk_mul_f32 v[24:25], v[24:25], v[130:131] op_sel_hi:[1,0]
	v_pk_mul_f32 v[22:23], v[22:23], v[130:131] op_sel_hi:[1,0]
	v_pk_mul_f32 v[20:21], v[20:21], v[130:131] op_sel_hi:[1,0]
	v_pk_mul_f32 v[18:19], v[18:19], v[130:131] op_sel_hi:[1,0]
	v_pk_mul_f32 v[16:17], v[16:17], v[130:131] op_sel_hi:[1,0]
	v_pk_mul_f32 v[14:15], v[14:15], v[130:131] op_sel_hi:[1,0]
	v_pk_mul_f32 v[12:13], v[12:13], v[130:131] op_sel_hi:[1,0]
	v_pk_mul_f32 v[10:11], v[10:11], v[130:131] op_sel_hi:[1,0]
	v_pk_mul_f32 v[8:9], v[8:9], v[130:131] op_sel_hi:[1,0]
	v_pk_mul_f32 v[6:7], v[6:7], v[130:131] op_sel_hi:[1,0]
	v_pk_mul_f32 v[4:5], v[4:5], v[130:131] op_sel_hi:[1,0]
	v_pk_mul_f32 v[2:3], v[2:3], v[130:131] op_sel_hi:[1,0]

.LBB0_1005:
	s_nop 0
	v_max3_f32 v64, v171, v169, v52
	v_max3_f32 v64, v64, v166, v53
	v_max3_f32 v64, v64, v167, v168
	v_max3_f32 v64, v64, v170, v54
	v_max3_f32 v64, v64, v164, v55
	v_max3_f32 v64, v64, v165, v56
	v_max3_f32 v64, v64, v162, v57
	v_max3_f32 v64, v64, v163, v58
	v_max3_f32 v64, v64, v160, v59
	v_max3_f32 v64, v64, v161, v60
	v_max3_f32 v64, v64, v158, v61
	v_max3_f32 v64, v64, v159, v62
	v_max3_f32 v64, v64, v156, v63
	v_max3_f32 v64, v64, v157, v50
	v_max3_f32 v64, v64, v154, v51
	v_max_f32_e32 v64, v64, v155
	v_sub_f32_e32 v65, v181, v64
	v_cmp_gt_f32_e32 vcc, 0xc1000000, v65
	s_cbranch_vccnz .Llazy3_full
	s_waitcnt lgkmcnt(0)
	v_mov_b32_e32 v182, v181
	v_mov_b32_e32 v64, 1.0
	s_branch .LBB0_1007
.Llazy3_full:
	v_and_b32_e32 v182, 64, v218
	v_xor_b32_e32 v65, 32, v218
	v_add_u32_e32 v182, 64, v182
	v_cmp_lt_i32_e32 vcc, v65, v182
	s_nop 1
	v_cndmask_b32_e32 v65, v218, v65, vcc
	v_lshlrev_b32_e32 v65, 2, v65
	ds_bpermute_b32 v65, v65, v64
	s_waitcnt lgkmcnt(0)
	v_max3_f32 v182, v181, v64, v65
	v_sub_f32_e32 v64, v181, v182
	v_exp_f32_e32 v64, v64
	s_nop 0
	v_cmp_neq_f32_e32 vcc, 1.0, v64
	s_cbranch_vccz .LBB0_1007
	v_pk_mul_f32 v[18:19], v[18:19], v[64:65] op_sel_hi:[1,0]
	v_pk_mul_f32 v[16:17], v[16:17], v[64:65] op_sel_hi:[1,0]
	v_pk_mul_f32 v[14:15], v[14:15], v[64:65] op_sel_hi:[1,0]
	v_pk_mul_f32 v[12:13], v[12:13], v[64:65] op_sel_hi:[1,0]
	v_pk_mul_f32 v[10:11], v[10:11], v[64:65] op_sel_hi:[1,0]
	v_pk_mul_f32 v[8:9], v[8:9], v[64:65] op_sel_hi:[1,0]
	v_pk_mul_f32 v[6:7], v[6:7], v[64:65] op_sel_hi:[1,0]
	v_pk_mul_f32 v[4:5], v[4:5], v[64:65] op_sel_hi:[1,0]
	v_pk_mul_f32 v[40:41], v[40:41], v[64:65] op_sel_hi:[1,0]
	v_pk_mul_f32 v[38:39], v[38:39], v[64:65] op_sel_hi:[1,0]
	v_pk_mul_f32 v[36:37], v[36:37], v[64:65] op_sel_hi:[1,0]
	v_pk_mul_f32 v[34:35], v[34:35], v[64:65] op_sel_hi:[1,0]
	v_pk_mul_f32 v[32:33], v[32:33], v[64:65] op_sel_hi:[1,0]
	v_pk_mul_f32 v[30:31], v[30:31], v[64:65] op_sel_hi:[1,0]
	v_pk_mul_f32 v[28:29], v[28:29], v[64:65] op_sel_hi:[1,0]
	v_pk_mul_f32 v[26:27], v[26:27], v[64:65] op_sel_hi:[1,0]

.LBB0_1051:
	s_waitcnt lgkmcnt(0)
	s_nop 3
	s_nop 0
	v_max3_f32 v178, v99, v115, v100
	v_max3_f32 v178, v178, v116, v101
	v_max3_f32 v178, v178, v117, v114
	v_max3_f32 v178, v178, v98, v102
	v_max3_f32 v178, v178, v118, v103
	v_max3_f32 v178, v178, v119, v104
	v_max3_f32 v178, v178, v120, v105
	v_max3_f32 v178, v178, v121, v106
	v_max3_f32 v178, v178, v122, v107
	v_max3_f32 v178, v178, v123, v108
	v_max3_f32 v178, v178, v124, v109
	v_max3_f32 v178, v178, v125, v110
	v_max3_f32 v178, v178, v126, v111
	v_max3_f32 v178, v178, v127, v112
	v_max3_f32 v178, v178, v128, v113
	v_max_f32_e32 v178, v178, v129
	v_sub_f32_e32 v179, v205, v178
	v_cmp_gt_f32_e32 vcc, 0xc1000000, v179
	s_cbranch_vccnz .Llazy4_full
	s_waitcnt lgkmcnt(0)
	v_mov_b32_e32 v207, v205
	v_mov_b32_e32 v178, 1.0
	s_branch .LBB0_1053
.Llazy4_full:
	v_and_b32_e32 v180, 64, v218
	v_xor_b32_e32 v179, 32, v218
	v_add_u32_e32 v180, 64, v180
	v_cmp_lt_i32_e32 vcc, v179, v180
	s_nop 1
	v_cndmask_b32_e32 v179, v218, v179, vcc
	v_lshlrev_b32_e32 v179, 2, v179
	ds_bpermute_b32 v179, v179, v178
	s_waitcnt lgkmcnt(0)
	v_max3_f32 v207, v205, v178, v179
	v_sub_f32_e32 v178, v205, v207
	v_exp_f32_e32 v178, v178
	s_nop 0
	v_cmp_neq_f32_e32 vcc, 1.0, v178
	s_cbranch_vccz .LBB0_1053
	v_pk_mul_f32 v[64:65], v[64:65], v[178:179] op_sel_hi:[1,0]
	v_pk_mul_f32 v[62:63], v[62:63], v[178:179] op_sel_hi:[1,0]
	v_pk_mul_f32 v[60:61], v[60:61], v[178:179] op_sel_hi:[1,0]
	v_pk_mul_f32 v[58:59], v[58:59], v[178:179] op_sel_hi:[1,0]
	v_pk_mul_f32 v[56:57], v[56:57], v[178:179] op_sel_hi:[1,0]
	v_pk_mul_f32 v[54:55], v[54:55], v[178:179] op_sel_hi:[1,0]
	v_pk_mul_f32 v[52:53], v[52:53], v[178:179] op_sel_hi:[1,0]
	v_pk_mul_f32 v[50:51], v[50:51], v[178:179] op_sel_hi:[1,0]
	v_pk_mul_f32 v[48:49], v[48:49], v[178:179] op_sel_hi:[1,0]
	v_pk_mul_f32 v[46:47], v[46:47], v[178:179] op_sel_hi:[1,0]
	v_pk_mul_f32 v[44:45], v[44:45], v[178:179] op_sel_hi:[1,0]
	v_pk_mul_f32 v[42:43], v[42:43], v[178:179] op_sel_hi:[1,0]
	v_pk_mul_f32 v[40:41], v[40:41], v[178:179] op_sel_hi:[1,0]
	v_pk_mul_f32 v[38:39], v[38:39], v[178:179] op_sel_hi:[1,0]
	v_pk_mul_f32 v[36:37], v[36:37], v[178:179] op_sel_hi:[1,0]
	v_pk_mul_f32 v[34:35], v[34:35], v[178:179] op_sel_hi:[1,0]

.LBB0_1067:
	s_nop 3
	s_nop 0
	v_max3_f32 v114, v83, v67, v84
	v_max3_f32 v114, v114, v68, v85
	v_max3_f32 v114, v114, v69, v66
	v_max3_f32 v114, v114, v82, v86
	v_max3_f32 v114, v114, v70, v87
	v_max3_f32 v114, v114, v71, v88
	v_max3_f32 v114, v114, v72, v89
	v_max3_f32 v114, v114, v73, v90
	v_max3_f32 v114, v114, v74, v91
	v_max3_f32 v114, v114, v75, v92
	v_max3_f32 v114, v114, v76, v93
	v_max3_f32 v114, v114, v77, v94
	v_max3_f32 v114, v114, v78, v95
	v_max3_f32 v114, v114, v79, v96
	v_max3_f32 v114, v114, v80, v97
	v_max_f32_e32 v114, v114, v81
	v_sub_f32_e32 v115, v204, v114
	v_cmp_gt_f32_e32 vcc, 0xc1000000, v115
	s_cbranch_vccnz .Llazy5_full
	s_waitcnt lgkmcnt(0)
	v_mov_b32_e32 v206, v204
	v_mov_b32_e32 v114, 1.0
	s_branch .LBB0_1069
.Llazy5_full:
	v_and_b32_e32 v116, 64, v218
	v_xor_b32_e32 v115, 32, v218
	v_add_u32_e32 v116, 64, v116
	v_cmp_lt_i32_e32 vcc, v115, v116
	s_nop 1
	v_cndmask_b32_e32 v115, v218, v115, vcc
	v_lshlrev_b32_e32 v115, 2, v115
	ds_bpermute_b32 v115, v115, v114
	s_waitcnt lgkmcnt(0)
	v_max3_f32 v206, v204, v114, v115
	v_sub_f32_e32 v114, v204, v206
	v_exp_f32_e32 v114, v114
	s_nop 0
	v_cmp_neq_f32_e32 vcc, 1.0, v114
	s_cbranch_vccz .LBB0_1069
	v_pk_mul_f32 v[16:17], v[16:17], v[114:115] op_sel_hi:[1,0]
	v_pk_mul_f32 v[14:15], v[14:15], v[114:115] op_sel_hi:[1,0]
	v_pk_mul_f32 v[12:13], v[12:13], v[114:115] op_sel_hi:[1,0]
	v_pk_mul_f32 v[10:11], v[10:11], v[114:115] op_sel_hi:[1,0]
	v_pk_mul_f32 v[8:9], v[8:9], v[114:115] op_sel_hi:[1,0]
	v_pk_mul_f32 v[6:7], v[6:7], v[114:115] op_sel_hi:[1,0]
	v_pk_mul_f32 v[4:5], v[4:5], v[114:115] op_sel_hi:[1,0]
	v_pk_mul_f32 v[2:3], v[2:3], v[114:115] op_sel_hi:[1,0]
	v_pk_mul_f32 v[32:33], v[32:33], v[114:115] op_sel_hi:[1,0]
	v_pk_mul_f32 v[30:31], v[30:31], v[114:115] op_sel_hi:[1,0]
	v_pk_mul_f32 v[28:29], v[28:29], v[114:115] op_sel_hi:[1,0]
	v_pk_mul_f32 v[26:27], v[26:27], v[114:115] op_sel_hi:[1,0]
	v_pk_mul_f32 v[24:25], v[24:25], v[114:115] op_sel_hi:[1,0]
	v_pk_mul_f32 v[22:23], v[22:23], v[114:115] op_sel_hi:[1,0]
	v_pk_mul_f32 v[20:21], v[20:21], v[114:115] op_sel_hi:[1,0]
	v_pk_mul_f32 v[18:19], v[18:19], v[114:115] op_sel_hi:[1,0]

.LBB0_1107:
	s_waitcnt lgkmcnt(0)
	s_nop 3
	s_nop 0
	v_max3_f32 v178, v99, v115, v100
	v_max3_f32 v178, v178, v116, v101
	v_max3_f32 v178, v178, v117, v114
	v_max3_f32 v178, v178, v98, v102
	v_max3_f32 v178, v178, v118, v103
	v_max3_f32 v178, v178, v119, v104
	v_max3_f32 v178, v178, v120, v105
	v_max3_f32 v178, v178, v121, v106
	v_max3_f32 v178, v178, v122, v107
	v_max3_f32 v178, v178, v123, v108
	v_max3_f32 v178, v178, v124, v109
	v_max3_f32 v178, v178, v125, v110
	v_max3_f32 v178, v178, v126, v111
	v_max3_f32 v178, v178, v127, v112
	v_max3_f32 v178, v178, v128, v113
	v_max_f32_e32 v178, v178, v129
	v_sub_f32_e32 v179, v207, v178
	v_cmp_gt_f32_e32 vcc, 0xc1000000, v179
	s_cbranch_vccnz .Llazy6_full
	s_waitcnt lgkmcnt(0)
	v_mov_b32_e32 v205, v207
	v_mov_b32_e32 v178, 1.0
	s_branch .LBB0_1109
.Llazy6_full:
	v_and_b32_e32 v180, 64, v218
	v_xor_b32_e32 v179, 32, v218
	v_add_u32_e32 v180, 64, v180
	v_cmp_lt_i32_e32 vcc, v179, v180
	s_nop 1
	v_cndmask_b32_e32 v179, v218, v179, vcc
	v_lshlrev_b32_e32 v179, 2, v179
	ds_bpermute_b32 v179, v179, v178
	s_waitcnt lgkmcnt(0)
	v_max3_f32 v205, v207, v178, v179
	v_sub_f32_e32 v178, v207, v205
	v_exp_f32_e32 v178, v178
	s_nop 0
	v_cmp_neq_f32_e32 vcc, 1.0, v178
	s_cbranch_vccz .LBB0_1109
	v_pk_mul_f32 v[64:65], v[64:65], v[178:179] op_sel_hi:[1,0]
	v_pk_mul_f32 v[62:63], v[62:63], v[178:179] op_sel_hi:[1,0]
	v_pk_mul_f32 v[60:61], v[60:61], v[178:179] op_sel_hi:[1,0]
	v_pk_mul_f32 v[58:59], v[58:59], v[178:179] op_sel_hi:[1,0]
	v_pk_mul_f32 v[56:57], v[56:57], v[178:179] op_sel_hi:[1,0]
	v_pk_mul_f32 v[54:55], v[54:55], v[178:179] op_sel_hi:[1,0]
	v_pk_mul_f32 v[52:53], v[52:53], v[178:179] op_sel_hi:[1,0]
	v_pk_mul_f32 v[50:51], v[50:51], v[178:179] op_sel_hi:[1,0]
	v_pk_mul_f32 v[48:49], v[48:49], v[178:179] op_sel_hi:[1,0]
	v_pk_mul_f32 v[46:47], v[46:47], v[178:179] op_sel_hi:[1,0]
	v_pk_mul_f32 v[44:45], v[44:45], v[178:179] op_sel_hi:[1,0]
	v_pk_mul_f32 v[42:43], v[42:43], v[178:179] op_sel_hi:[1,0]
	v_pk_mul_f32 v[40:41], v[40:41], v[178:179] op_sel_hi:[1,0]
	v_pk_mul_f32 v[38:39], v[38:39], v[178:179] op_sel_hi:[1,0]
	v_pk_mul_f32 v[36:37], v[36:37], v[178:179] op_sel_hi:[1,0]
	v_pk_mul_f32 v[34:35], v[34:35], v[178:179] op_sel_hi:[1,0]

.LBB0_1124:
	s_nop 3
	s_nop 0
	v_max3_f32 v114, v83, v67, v84
	v_max3_f32 v114, v114, v68, v85
	v_max3_f32 v114, v114, v69, v66
	v_max3_f32 v114, v114, v82, v86
	v_max3_f32 v114, v114, v70, v87
	v_max3_f32 v114, v114, v71, v88
	v_max3_f32 v114, v114, v72, v89
	v_max3_f32 v114, v114, v73, v90
	v_max3_f32 v114, v114, v74, v91
	v_max3_f32 v114, v114, v75, v92
	v_max3_f32 v114, v114, v76, v93
	v_max3_f32 v114, v114, v77, v94
	v_max3_f32 v114, v114, v78, v95
	v_max3_f32 v114, v114, v79, v96
	v_max3_f32 v114, v114, v80, v97
	v_max_f32_e32 v114, v114, v81
	v_sub_f32_e32 v115, v206, v114
	v_cmp_gt_f32_e32 vcc, 0xc1000000, v115
	s_cbranch_vccnz .Llazy7_full
	s_waitcnt lgkmcnt(0)
	v_mov_b32_e32 v204, v206
	v_mov_b32_e32 v114, 1.0
	s_branch .LBB0_1126
.Llazy7_full:
	v_and_b32_e32 v116, 64, v218
	v_xor_b32_e32 v115, 32, v218
	v_add_u32_e32 v116, 64, v116
	v_cmp_lt_i32_e32 vcc, v115, v116
	s_nop 1
	v_cndmask_b32_e32 v115, v218, v115, vcc
	v_lshlrev_b32_e32 v115, 2, v115
	ds_bpermute_b32 v115, v115, v114
	s_waitcnt lgkmcnt(0)
	v_max3_f32 v204, v206, v114, v115
	v_sub_f32_e32 v114, v206, v204
	v_exp_f32_e32 v114, v114
	s_nop 0
	v_cmp_neq_f32_e32 vcc, 1.0, v114
	s_cbranch_vccz .LBB0_1126
	v_pk_mul_f32 v[16:17], v[16:17], v[114:115] op_sel_hi:[1,0]
	v_pk_mul_f32 v[14:15], v[14:15], v[114:115] op_sel_hi:[1,0]
	v_pk_mul_f32 v[12:13], v[12:13], v[114:115] op_sel_hi:[1,0]
	v_pk_mul_f32 v[10:11], v[10:11], v[114:115] op_sel_hi:[1,0]
	v_pk_mul_f32 v[8:9], v[8:9], v[114:115] op_sel_hi:[1,0]
	v_pk_mul_f32 v[6:7], v[6:7], v[114:115] op_sel_hi:[1,0]
	v_pk_mul_f32 v[4:5], v[4:5], v[114:115] op_sel_hi:[1,0]
	v_pk_mul_f32 v[2:3], v[2:3], v[114:115] op_sel_hi:[1,0]
	v_pk_mul_f32 v[32:33], v[32:33], v[114:115] op_sel_hi:[1,0]
	v_pk_mul_f32 v[30:31], v[30:31], v[114:115] op_sel_hi:[1,0]
	v_pk_mul_f32 v[28:29], v[28:29], v[114:115] op_sel_hi:[1,0]
	v_pk_mul_f32 v[26:27], v[26:27], v[114:115] op_sel_hi:[1,0]
	v_pk_mul_f32 v[24:25], v[24:25], v[114:115] op_sel_hi:[1,0]
	v_pk_mul_f32 v[22:23], v[22:23], v[114:115] op_sel_hi:[1,0]
	v_pk_mul_f32 v[20:21], v[20:21], v[114:115] op_sel_hi:[1,0]
	v_pk_mul_f32 v[18:19], v[18:19], v[114:115] op_sel_hi:[1,0]

.LBB0_1165:
	s_sub_i32 s45, s42, 64
	s_cmp_ge_u32 s45, s66
	s_cselect_b64 s[48:49], -1, 0
	s_cmp_gt_i32 s44, s39
	s_cselect_b64 s[50:51], -1, 0
	s_or_b64 s[48:49], s[50:51], s[48:49]
	s_and_b64 vcc, exec, s[48:49]
	s_cbranch_vccnz .LBB0_1169
	v_add_u32_e32 v120, v124, v198
	ds_read_b128 v[136:139], v120
	ds_read_b128 v[140:143], v120 offset:6656
	ds_read_b128 v[144:147], v120 offset:32
	ds_read_b128 v[148:151], v120 offset:6688
	ds_read_b128 v[152:155], v120 offset:64
	ds_read_b128 v[156:159], v120 offset:6720
	ds_read_b128 v[160:163], v120 offset:96
	ds_read_b128 v[164:167], v120 offset:6752
	ds_read_b128 v[168:171], v120 offset:128
	ds_read_b128 v[172:175], v120 offset:6784
	ds_read_b128 v[176:179], v120 offset:160
	ds_read_b128 v[180:183], v120 offset:6816
	v_add_u32_e32 v184, v125, v126
	s_waitcnt lgkmcnt(11)
	v_mfma_f32_32x32x16_bf16 v[34:49], v[136:139], v[66:69], 0
	s_waitcnt lgkmcnt(10)
	v_mfma_f32_32x32x16_bf16 v[50:65], v[140:143], v[66:69], 0
	s_waitcnt lgkmcnt(9)
	v_mfma_f32_32x32x16_bf16 v[34:49], v[144:147], v[70:73], v[34:49]
	s_waitcnt lgkmcnt(8)
	v_mfma_f32_32x32x16_bf16 v[50:65], v[148:151], v[70:73], v[50:65]
	s_waitcnt lgkmcnt(7)
	v_mfma_f32_32x32x16_bf16 v[34:49], v[152:155], v[74:77], v[34:49]
	s_waitcnt lgkmcnt(6)
	v_mfma_f32_32x32x16_bf16 v[50:65], v[156:159], v[74:77], v[50:65]
	s_waitcnt lgkmcnt(5)
	v_mfma_f32_32x32x16_bf16 v[34:49], v[160:163], v[78:81], v[34:49]
	s_waitcnt lgkmcnt(4)
	v_mfma_f32_32x32x16_bf16 v[50:65], v[164:167], v[78:81], v[50:65]
	s_waitcnt lgkmcnt(3)
	v_mfma_f32_32x32x16_bf16 v[34:49], v[168:171], v[106:109], v[34:49]
	s_waitcnt lgkmcnt(2)
	v_mfma_f32_32x32x16_bf16 v[50:65], v[172:175], v[106:109], v[50:65]
	s_waitcnt lgkmcnt(1)
	v_mfma_f32_32x32x16_bf16 v[34:49], v[176:179], v[110:113], v[34:49]
	s_waitcnt lgkmcnt(0)
	v_mfma_f32_32x32x16_bf16 v[50:65], v[180:183], v[110:113], v[50:65]
	s_nop 11
	v_max3_f32 v120, v34, v35, v36
	v_max3_f32 v120, v120, v37, v38
	v_max3_f32 v120, v120, v39, v40
	v_max3_f32 v120, v120, v41, v42
	v_max3_f32 v120, v120, v43, v44
	v_max3_f32 v120, v120, v45, v46
	v_max3_f32 v120, v120, v47, v48
	v_max3_f32 v120, v120, v49, v50
	v_max3_f32 v120, v120, v51, v52
	v_max3_f32 v120, v120, v53, v54
	v_max3_f32 v120, v120, v55, v56
	v_max3_f32 v120, v120, v57, v58
	v_max3_f32 v120, v120, v59, v60
	v_max3_f32 v120, v120, v61, v62
	v_max3_f32 v120, v120, v63, v64
	v_max_f32_e32 v120, v120, v65
	v_sub_f32_e32 v130, v129, v120
	v_cmp_gt_f32_e32 vcc, 0xc1000000, v130
	s_cbranch_vccnz .Llazy8_full
	ds_read_b64_tr_b16 v[136:137], v184 offset:13312
	ds_read_b64_tr_b16 v[138:139], v184 offset:14464
	ds_read_b64_tr_b16 v[140:141], v184 offset:13376
	ds_read_b64_tr_b16 v[142:143], v184 offset:14528
	ds_read_b64_tr_b16 v[144:145], v184 offset:15616
	ds_read_b64_tr_b16 v[146:147], v184 offset:16768
	ds_read_b64_tr_b16 v[148:149], v184 offset:15680
	ds_read_b64_tr_b16 v[150:151], v184 offset:16832
	ds_read_b64_tr_b16 v[152:153], v184 offset:17920
	ds_read_b64_tr_b16 v[154:155], v184 offset:19072
	ds_read_b64_tr_b16 v[156:157], v184 offset:17984
	ds_read_b64_tr_b16 v[158:159], v184 offset:19136
	ds_read_b64_tr_b16 v[160:161], v184 offset:20224
	ds_read_b64_tr_b16 v[162:163], v184 offset:21376
	ds_read_b64_tr_b16 v[164:165], v184 offset:20288
	ds_read_b64_tr_b16 v[166:167], v184 offset:21440
	v_mov_b32_e32 v130, v129
	v_mov_b32_e32 v120, 1.0
	s_branch .LBB0_1168
.Llazy8_full:
	v_and_b32_e32 v131, 64, v218
	v_xor_b32_e32 v130, 32, v218
	v_add_u32_e32 v131, 64, v131
	v_cmp_lt_i32_e32 vcc, v130, v131
	s_nop 1
	v_cndmask_b32_e32 v130, v218, v130, vcc
	v_lshlrev_b32_e32 v130, 2, v130
	ds_bpermute_b32 v130, v130, v120
	s_waitcnt lgkmcnt(0)
	ds_read_b64_tr_b16 v[136:137], v184 offset:13312
	ds_read_b64_tr_b16 v[138:139], v184 offset:14464
	ds_read_b64_tr_b16 v[140:141], v184 offset:13376
	ds_read_b64_tr_b16 v[142:143], v184 offset:14528
	ds_read_b64_tr_b16 v[144:145], v184 offset:15616
	ds_read_b64_tr_b16 v[146:147], v184 offset:16768
	ds_read_b64_tr_b16 v[148:149], v184 offset:15680
	ds_read_b64_tr_b16 v[150:151], v184 offset:16832
	ds_read_b64_tr_b16 v[152:153], v184 offset:17920
	ds_read_b64_tr_b16 v[154:155], v184 offset:19072
	ds_read_b64_tr_b16 v[156:157], v184 offset:17984
	ds_read_b64_tr_b16 v[158:159], v184 offset:19136
	ds_read_b64_tr_b16 v[160:161], v184 offset:20224
	ds_read_b64_tr_b16 v[162:163], v184 offset:21376
	ds_read_b64_tr_b16 v[164:165], v184 offset:20288
	ds_read_b64_tr_b16 v[166:167], v184 offset:21440
	v_max3_f32 v130, v129, v120, v130
	v_sub_f32_e32 v120, v129, v130
	v_exp_f32_e32 v120, v120
	s_nop 0
	v_cmp_neq_f32_e32 vcc, 1.0, v120
	s_cbranch_vccz .LBB0_1168
	v_pk_mul_f32 v[16:17], v[16:17], v[120:121] op_sel_hi:[1,0]
	v_pk_mul_f32 v[14:15], v[14:15], v[120:121] op_sel_hi:[1,0]
	v_pk_mul_f32 v[12:13], v[12:13], v[120:121] op_sel_hi:[1,0]
	v_pk_mul_f32 v[10:11], v[10:11], v[120:121] op_sel_hi:[1,0]
	v_pk_mul_f32 v[8:9], v[8:9], v[120:121] op_sel_hi:[1,0]
	v_pk_mul_f32 v[6:7], v[6:7], v[120:121] op_sel_hi:[1,0]
	v_pk_mul_f32 v[4:5], v[4:5], v[120:121] op_sel_hi:[1,0]
	v_pk_mul_f32 v[2:3], v[2:3], v[120:121] op_sel_hi:[1,0]
	v_pk_mul_f32 v[32:33], v[32:33], v[120:121] op_sel_hi:[1,0]
	v_pk_mul_f32 v[30:31], v[30:31], v[120:121] op_sel_hi:[1,0]
	v_pk_mul_f32 v[28:29], v[28:29], v[120:121] op_sel_hi:[1,0]
	v_pk_mul_f32 v[26:27], v[26:27], v[120:121] op_sel_hi:[1,0]
	v_pk_mul_f32 v[24:25], v[24:25], v[120:121] op_sel_hi:[1,0]
	v_pk_mul_f32 v[22:23], v[22:23], v[120:121] op_sel_hi:[1,0]
	v_pk_mul_f32 v[20:21], v[20:21], v[120:121] op_sel_hi:[1,0]
	v_pk_mul_f32 v[18:19], v[18:19], v[120:121] op_sel_hi:[1,0]

.LBB0_1179:
	s_cmp_ge_u32 s42, s66
	s_cselect_b64 s[48:49], -1, 0
	s_cmp_ge_i32 s44, s39
	s_cselect_b64 s[50:51], -1, 0
	s_or_b64 s[48:49], s[50:51], s[48:49]
	s_and_b64 vcc, exec, s[48:49]
	s_cbranch_vccnz .LBB0_1184
	v_add_u32_e32 v120, v124, v198
	ds_read_b128 v[136:139], v120 offset:32768
	ds_read_b128 v[140:143], v120 offset:39424
	ds_read_b128 v[144:147], v120 offset:32800
	ds_read_b128 v[148:151], v120 offset:39456
	ds_read_b128 v[152:155], v120 offset:32832
	ds_read_b128 v[156:159], v120 offset:39488
	ds_read_b128 v[160:163], v120 offset:32864
	ds_read_b128 v[164:167], v120 offset:39520
	ds_read_b128 v[168:171], v120 offset:32896
	ds_read_b128 v[172:175], v120 offset:39552
	ds_read_b128 v[176:179], v120 offset:32928
	ds_read_b128 v[180:183], v120 offset:39584
	v_add_u32_e32 v184, v125, v126
	s_waitcnt lgkmcnt(11)
	v_mfma_f32_32x32x16_bf16 v[34:49], v[136:139], v[66:69], 0
	s_waitcnt lgkmcnt(10)
	v_mfma_f32_32x32x16_bf16 v[50:65], v[140:143], v[66:69], 0
	s_waitcnt lgkmcnt(9)
	v_mfma_f32_32x32x16_bf16 v[34:49], v[144:147], v[70:73], v[34:49]
	s_waitcnt lgkmcnt(8)
	v_mfma_f32_32x32x16_bf16 v[50:65], v[148:151], v[70:73], v[50:65]
	s_waitcnt lgkmcnt(7)
	v_mfma_f32_32x32x16_bf16 v[34:49], v[152:155], v[74:77], v[34:49]
	s_waitcnt lgkmcnt(6)
	v_mfma_f32_32x32x16_bf16 v[50:65], v[156:159], v[74:77], v[50:65]
	s_waitcnt lgkmcnt(5)
	v_mfma_f32_32x32x16_bf16 v[34:49], v[160:163], v[78:81], v[34:49]
	s_waitcnt lgkmcnt(4)
	v_mfma_f32_32x32x16_bf16 v[50:65], v[164:167], v[78:81], v[50:65]
	s_waitcnt lgkmcnt(3)
	v_mfma_f32_32x32x16_bf16 v[34:49], v[168:171], v[106:109], v[34:49]
	s_waitcnt lgkmcnt(2)
	v_mfma_f32_32x32x16_bf16 v[50:65], v[172:175], v[106:109], v[50:65]
	s_waitcnt lgkmcnt(1)
	v_mfma_f32_32x32x16_bf16 v[34:49], v[176:179], v[110:113], v[34:49]
	s_waitcnt lgkmcnt(0)
	v_mfma_f32_32x32x16_bf16 v[50:65], v[180:183], v[110:113], v[50:65]
	s_nop 11
	v_max3_f32 v120, v34, v35, v36
	v_max3_f32 v120, v120, v37, v38
	v_max3_f32 v120, v120, v39, v40
	v_max3_f32 v120, v120, v41, v42
	v_max3_f32 v120, v120, v43, v44
	v_max3_f32 v120, v120, v45, v46
	v_max3_f32 v120, v120, v47, v48
	v_max3_f32 v120, v120, v49, v50
	v_max3_f32 v120, v120, v51, v52
	v_max3_f32 v120, v120, v53, v54
	v_max3_f32 v120, v120, v55, v56
	v_max3_f32 v120, v120, v57, v58
	v_max3_f32 v120, v120, v59, v60
	v_max3_f32 v120, v120, v61, v62
	v_max3_f32 v120, v120, v63, v64
	v_max_f32_e32 v120, v120, v65
	v_sub_f32_e32 v129, v130, v120
	v_cmp_gt_f32_e32 vcc, 0xc1000000, v129
	s_cbranch_vccnz .Llazy9_full
	ds_read_b64_tr_b16 v[136:137], v184 offset:46080
	ds_read_b64_tr_b16 v[138:139], v184 offset:47232
	ds_read_b64_tr_b16 v[140:141], v184 offset:46144
	ds_read_b64_tr_b16 v[142:143], v184 offset:47296
	ds_read_b64_tr_b16 v[144:145], v184 offset:48384
	ds_read_b64_tr_b16 v[146:147], v184 offset:49536
	ds_read_b64_tr_b16 v[148:149], v184 offset:48448
	ds_read_b64_tr_b16 v[150:151], v184 offset:49600
	ds_read_b64_tr_b16 v[152:153], v184 offset:50688
	ds_read_b64_tr_b16 v[154:155], v184 offset:51840
	ds_read_b64_tr_b16 v[156:157], v184 offset:50752
	ds_read_b64_tr_b16 v[158:159], v184 offset:51904
	ds_read_b64_tr_b16 v[160:161], v184 offset:52992
	ds_read_b64_tr_b16 v[162:163], v184 offset:54144
	ds_read_b64_tr_b16 v[164:165], v184 offset:53056
	ds_read_b64_tr_b16 v[166:167], v184 offset:54208
	v_mov_b32_e32 v129, v130
	v_mov_b32_e32 v120, 1.0
	s_branch .LBB0_1182
.Llazy9_full:
	v_and_b32_e32 v131, 64, v218
	v_xor_b32_e32 v129, 32, v218
	v_add_u32_e32 v131, 64, v131
	v_cmp_lt_i32_e32 vcc, v129, v131
	s_nop 1
	v_cndmask_b32_e32 v129, v218, v129, vcc
	v_lshlrev_b32_e32 v129, 2, v129
	ds_bpermute_b32 v129, v129, v120
	s_waitcnt lgkmcnt(0)
	ds_read_b64_tr_b16 v[136:137], v184 offset:46080
	ds_read_b64_tr_b16 v[138:139], v184 offset:47232
	ds_read_b64_tr_b16 v[140:141], v184 offset:46144
	ds_read_b64_tr_b16 v[142:143], v184 offset:47296
	ds_read_b64_tr_b16 v[144:145], v184 offset:48384
	ds_read_b64_tr_b16 v[146:147], v184 offset:49536
	ds_read_b64_tr_b16 v[148:149], v184 offset:48448
	ds_read_b64_tr_b16 v[150:151], v184 offset:49600
	ds_read_b64_tr_b16 v[152:153], v184 offset:50688
	ds_read_b64_tr_b16 v[154:155], v184 offset:51840
	ds_read_b64_tr_b16 v[156:157], v184 offset:50752
	ds_read_b64_tr_b16 v[158:159], v184 offset:51904
	ds_read_b64_tr_b16 v[160:161], v184 offset:52992
	ds_read_b64_tr_b16 v[162:163], v184 offset:54144
	ds_read_b64_tr_b16 v[164:165], v184 offset:53056
	ds_read_b64_tr_b16 v[166:167], v184 offset:54208
	v_max3_f32 v129, v130, v120, v129
	v_sub_f32_e32 v120, v130, v129
	v_exp_f32_e32 v120, v120
	s_nop 0
	v_cmp_neq_f32_e32 vcc, 1.0, v120
	s_cbranch_vccz .LBB0_1182
	v_pk_mul_f32 v[16:17], v[16:17], v[120:121] op_sel_hi:[1,0]
	v_pk_mul_f32 v[14:15], v[14:15], v[120:121] op_sel_hi:[1,0]
	v_pk_mul_f32 v[12:13], v[12:13], v[120:121] op_sel_hi:[1,0]
	v_pk_mul_f32 v[10:11], v[10:11], v[120:121] op_sel_hi:[1,0]
	v_pk_mul_f32 v[8:9], v[8:9], v[120:121] op_sel_hi:[1,0]
	v_pk_mul_f32 v[6:7], v[6:7], v[120:121] op_sel_hi:[1,0]
	v_pk_mul_f32 v[4:5], v[4:5], v[120:121] op_sel_hi:[1,0]
	v_pk_mul_f32 v[2:3], v[2:3], v[120:121] op_sel_hi:[1,0]
	v_pk_mul_f32 v[32:33], v[32:33], v[120:121] op_sel_hi:[1,0]
	v_pk_mul_f32 v[30:31], v[30:31], v[120:121] op_sel_hi:[1,0]
	v_pk_mul_f32 v[28:29], v[28:29], v[120:121] op_sel_hi:[1,0]
	v_pk_mul_f32 v[26:27], v[26:27], v[120:121] op_sel_hi:[1,0]
	v_pk_mul_f32 v[24:25], v[24:25], v[120:121] op_sel_hi:[1,0]
	v_pk_mul_f32 v[22:23], v[22:23], v[120:121] op_sel_hi:[1,0]
	v_pk_mul_f32 v[20:21], v[20:21], v[120:121] op_sel_hi:[1,0]
	v_pk_mul_f32 v[18:19], v[18:19], v[120:121] op_sel_hi:[1,0]
